# select fast path: candidate compaction rewritten as straight-line predicated code with running LDS addresses (8 instr per element instead of branch + 11)
# speedup vs baseline: 1.0188x; 1.0017x over previous
.LBB0_1206:
	s_and_b64 vcc, exec, s[6:7]
	s_cbranch_vccz .LBB0_531
	s_cmp_gt_i32 s84, 7
	v_cndmask_b32_e64 v0, v69, v68, s[4:5]
	s_cselect_b64 vcc, -1, 0
	s_cmp_gt_i32 s84, 6
	v_cndmask_b32_e32 v0, 0, v0, vcc
	v_cndmask_b32_e64 v1, v67, v66, s[4:5]
	s_cselect_b64 vcc, -1, 0
	s_cmp_gt_i32 s84, 5
	v_cndmask_b32_e32 v1, 0, v1, vcc
	v_cndmask_b32_e64 v5, v65, v64, s[4:5]
	s_cselect_b64 vcc, -1, 0
	s_cmp_gt_i32 s84, 4
	v_cndmask_b32_e32 v5, 0, v5, vcc
	v_cndmask_b32_e64 v6, v63, v62, s[4:5]
	s_cselect_b64 vcc, -1, 0
	s_cmp_gt_i32 s84, 3
	v_cndmask_b32_e32 v6, 0, v6, vcc
	v_cndmask_b32_e64 v7, v61, v60, s[4:5]
	s_cselect_b64 vcc, -1, 0
	s_cmp_gt_i32 s84, 2
	v_cndmask_b32_e32 v7, 0, v7, vcc
	v_cndmask_b32_e64 v9, v59, v58, s[4:5]
	s_cselect_b64 vcc, -1, 0
	s_cmp_gt_i32 s84, 1
	v_cndmask_b32_e32 v9, 0, v9, vcc
	v_cndmask_b32_e64 v10, v57, v107, s[4:5]
	s_cselect_b64 vcc, -1, 0
	s_cmp_gt_i32 s84, 0
	v_cndmask_b32_e32 v10, 0, v10, vcc
	v_cndmask_b32_e64 v11, v106, v54, s[4:5]
	s_cselect_b64 vcc, -1, 0
	v_cndmask_b32_e32 v11, 0, v11, vcc
	v_sub_u32_e32 v12, v128, v127
	v_add3_u32 v10, v12, v11, v10
	v_add3_u32 v7, v10, v9, v7
	v_add3_u32 v5, v7, v6, v5
	v_add3_u32 v0, v5, v1, v0
	v_mov_b32_e32 v5, v126
	v_lshlrev_b32_e32 v1, 11, v131
	v_add_u32_e32 v0, v0, v1
	v_lshlrev_b32_e32 v6, 2, v0
	v_lshlrev_b32_e32 v7, 1, v0
	v_cmp_ge_u32_e32 vcc, v133, v5
	s_and_saveexec_b64 s[0:1], vcc
	ds_write_b32 v6, v133 offset:10496
	ds_write_b16 v7, v130 offset:26880
	v_add_u32_e32 v6, 4, v6
	v_add_u32_e32 v7, 2, v7
	s_mov_b64 exec, s[0:1]
	v_cmp_ge_u32_e32 vcc, v132, v5
	v_add_u16_e32 v9, 0x100, v130
	s_and_saveexec_b64 s[0:1], vcc
	ds_write_b32 v6, v132 offset:10496
	ds_write_b16 v7, v9 offset:26880
	v_add_u32_e32 v6, 4, v6
	v_add_u32_e32 v7, 2, v7
	s_mov_b64 exec, s[0:1]
	v_cmp_ge_u32_e32 vcc, v135, v5
	v_add_u16_e32 v9, 0x200, v130
	s_and_saveexec_b64 s[0:1], vcc
	ds_write_b32 v6, v135 offset:10496
	ds_write_b16 v7, v9 offset:26880
	v_add_u32_e32 v6, 4, v6
	v_add_u32_e32 v7, 2, v7
	s_mov_b64 exec, s[0:1]
	v_cmp_ge_u32_e32 vcc, v134, v5
	v_add_u16_e32 v9, 0x300, v130
	s_and_saveexec_b64 s[0:1], vcc
	ds_write_b32 v6, v134 offset:10496
	ds_write_b16 v7, v9 offset:26880
	v_add_u32_e32 v6, 4, v6
	v_add_u32_e32 v7, 2, v7
	s_mov_b64 exec, s[0:1]
	v_cmp_ge_u32_e32 vcc, v138, v5
	v_add_u16_e32 v9, 0x400, v130
	s_and_saveexec_b64 s[0:1], vcc
	ds_write_b32 v6, v138 offset:10496
	ds_write_b16 v7, v9 offset:26880
	v_add_u32_e32 v6, 4, v6
	v_add_u32_e32 v7, 2, v7
	s_mov_b64 exec, s[0:1]
	v_cmp_ge_u32_e32 vcc, v137, v5
	v_add_u16_e32 v9, 0x500, v130
	s_and_saveexec_b64 s[0:1], vcc
	ds_write_b32 v6, v137 offset:10496
	ds_write_b16 v7, v9 offset:26880
	v_add_u32_e32 v6, 4, v6
	v_add_u32_e32 v7, 2, v7
	s_mov_b64 exec, s[0:1]
	v_cmp_ge_u32_e32 vcc, v140, v5
	v_add_u16_e32 v9, 0x600, v130
	s_and_saveexec_b64 s[0:1], vcc
	ds_write_b32 v6, v140 offset:10496
	ds_write_b16 v7, v9 offset:26880
	v_add_u32_e32 v6, 4, v6
	v_add_u32_e32 v7, 2, v7
	s_mov_b64 exec, s[0:1]
	v_cmp_ge_u32_e32 vcc, v139, v5
	v_add_u16_e32 v9, 0x700, v130
	s_and_saveexec_b64 s[0:1], vcc
	ds_write_b32 v6, v139 offset:10496
	ds_write_b16 v7, v9 offset:26880
	v_add_u32_e32 v6, 4, v6
	v_add_u32_e32 v7, 2, v7
	s_mov_b64 exec, s[0:1]
	v_cmp_ge_u32_e32 vcc, v142, v5
	v_add_u16_e32 v9, 0x800, v130
	s_and_saveexec_b64 s[0:1], vcc
	ds_write_b32 v6, v142 offset:10496
	ds_write_b16 v7, v9 offset:26880
	v_add_u32_e32 v6, 4, v6
	v_add_u32_e32 v7, 2, v7
	s_mov_b64 exec, s[0:1]
	v_cmp_ge_u32_e32 vcc, v141, v5
	v_add_u16_e32 v9, 0x900, v130
	s_and_saveexec_b64 s[0:1], vcc
	ds_write_b32 v6, v141 offset:10496
	ds_write_b16 v7, v9 offset:26880
	v_add_u32_e32 v6, 4, v6
	v_add_u32_e32 v7, 2, v7
	s_mov_b64 exec, s[0:1]
	v_cmp_ge_u32_e32 vcc, v144, v5
	v_add_u16_e32 v9, 0xa00, v130
	s_and_saveexec_b64 s[0:1], vcc
	ds_write_b32 v6, v144 offset:10496
	ds_write_b16 v7, v9 offset:26880
	v_add_u32_e32 v6, 4, v6
	v_add_u32_e32 v7, 2, v7
	s_mov_b64 exec, s[0:1]
	v_cmp_ge_u32_e32 vcc, v143, v5
	v_add_u16_e32 v9, 0xb00, v130
	s_and_saveexec_b64 s[0:1], vcc
	ds_write_b32 v6, v143 offset:10496
	ds_write_b16 v7, v9 offset:26880
	v_add_u32_e32 v6, 4, v6
	v_add_u32_e32 v7, 2, v7
	s_mov_b64 exec, s[0:1]
	v_cmp_ge_u32_e32 vcc, v146, v5
	v_add_u16_e32 v9, 0xc00, v130
	s_and_saveexec_b64 s[0:1], vcc
	ds_write_b32 v6, v146 offset:10496
	ds_write_b16 v7, v9 offset:26880
	v_add_u32_e32 v6, 4, v6
	v_add_u32_e32 v7, 2, v7
	s_mov_b64 exec, s[0:1]
	v_cmp_ge_u32_e32 vcc, v145, v5
	v_add_u16_e32 v9, 0xd00, v130
	s_and_saveexec_b64 s[0:1], vcc
	ds_write_b32 v6, v145 offset:10496
	ds_write_b16 v7, v9 offset:26880
	v_add_u32_e32 v6, 4, v6
	v_add_u32_e32 v7, 2, v7
	s_mov_b64 exec, s[0:1]
	v_cmp_ge_u32_e32 vcc, v147, v5
	v_add_u16_e32 v9, 0xe00, v130
	s_and_saveexec_b64 s[0:1], vcc
	ds_write_b32 v6, v147 offset:10496
	ds_write_b16 v7, v9 offset:26880
	v_add_u32_e32 v6, 4, v6
	v_add_u32_e32 v7, 2, v7
	s_mov_b64 exec, s[0:1]
	v_cmp_ge_u32_e32 vcc, v136, v5
	v_add_u16_e32 v9, 0xf00, v130
	s_and_saveexec_b64 s[0:1], vcc
	ds_write_b32 v6, v136 offset:10496
	ds_write_b16 v7, v9 offset:26880
	v_add_u32_e32 v6, 4, v6
	v_add_u32_e32 v7, 2, v7
	s_mov_b64 exec, s[0:1]
	v_cmp_ge_u32_e32 vcc, v149, v5
	v_add_u16_e32 v9, 0x1000, v130
	s_and_saveexec_b64 s[0:1], vcc
	ds_write_b32 v6, v149 offset:10496
	ds_write_b16 v7, v9 offset:26880
	v_add_u32_e32 v6, 4, v6
	v_add_u32_e32 v7, 2, v7
	s_mov_b64 exec, s[0:1]
	v_cmp_ge_u32_e32 vcc, v148, v5
	v_add_u16_e32 v9, 0x1100, v130
	s_and_saveexec_b64 s[0:1], vcc
	ds_write_b32 v6, v148 offset:10496
	ds_write_b16 v7, v9 offset:26880
	v_add_u32_e32 v6, 4, v6
	v_add_u32_e32 v7, 2, v7
	s_mov_b64 exec, s[0:1]
	v_cmp_ge_u32_e32 vcc, v151, v5
	v_add_u16_e32 v9, 0x1200, v130
	s_and_saveexec_b64 s[0:1], vcc
	ds_write_b32 v6, v151 offset:10496
	ds_write_b16 v7, v9 offset:26880
	v_add_u32_e32 v6, 4, v6
	v_add_u32_e32 v7, 2, v7
	s_mov_b64 exec, s[0:1]
	v_cmp_ge_u32_e32 vcc, v150, v5
	v_add_u16_e32 v9, 0x1300, v130
	s_and_saveexec_b64 s[0:1], vcc
	ds_write_b32 v6, v150 offset:10496
	ds_write_b16 v7, v9 offset:26880
	v_add_u32_e32 v6, 4, v6
	v_add_u32_e32 v7, 2, v7
	s_mov_b64 exec, s[0:1]
	v_cmp_ge_u32_e32 vcc, v154, v5
	v_add_u16_e32 v9, 0x1400, v130
	s_and_saveexec_b64 s[0:1], vcc
	ds_write_b32 v6, v154 offset:10496
	ds_write_b16 v7, v9 offset:26880
	v_add_u32_e32 v6, 4, v6
	v_add_u32_e32 v7, 2, v7
	s_mov_b64 exec, s[0:1]
	v_cmp_ge_u32_e32 vcc, v153, v5
	v_add_u16_e32 v9, 0x1500, v130
	s_and_saveexec_b64 s[0:1], vcc
	ds_write_b32 v6, v153 offset:10496
	ds_write_b16 v7, v9 offset:26880
	v_add_u32_e32 v6, 4, v6
	v_add_u32_e32 v7, 2, v7
	s_mov_b64 exec, s[0:1]
	v_cmp_ge_u32_e32 vcc, v156, v5
	v_add_u16_e32 v9, 0x1600, v130
	s_and_saveexec_b64 s[0:1], vcc
	ds_write_b32 v6, v156 offset:10496
	ds_write_b16 v7, v9 offset:26880
	v_add_u32_e32 v6, 4, v6
	v_add_u32_e32 v7, 2, v7
	s_mov_b64 exec, s[0:1]
	v_cmp_ge_u32_e32 vcc, v155, v5
	v_add_u16_e32 v9, 0x1700, v130
	s_and_saveexec_b64 s[0:1], vcc
	ds_write_b32 v6, v155 offset:10496
	ds_write_b16 v7, v9 offset:26880
	v_add_u32_e32 v6, 4, v6
	v_add_u32_e32 v7, 2, v7
	s_mov_b64 exec, s[0:1]
	v_cmp_ge_u32_e32 vcc, v158, v5
	v_add_u16_e32 v9, 0x1800, v130
	s_and_saveexec_b64 s[0:1], vcc
	ds_write_b32 v6, v158 offset:10496
	ds_write_b16 v7, v9 offset:26880
	v_add_u32_e32 v6, 4, v6
	v_add_u32_e32 v7, 2, v7
	s_mov_b64 exec, s[0:1]
	v_cmp_ge_u32_e32 vcc, v157, v5
	v_add_u16_e32 v9, 0x1900, v130
	s_and_saveexec_b64 s[0:1], vcc
	ds_write_b32 v6, v157 offset:10496
	ds_write_b16 v7, v9 offset:26880
	v_add_u32_e32 v6, 4, v6
	v_add_u32_e32 v7, 2, v7
	s_mov_b64 exec, s[0:1]
	v_cmp_ge_u32_e32 vcc, v160, v5
	v_add_u16_e32 v9, 0x1a00, v130
	s_and_saveexec_b64 s[0:1], vcc
	ds_write_b32 v6, v160 offset:10496
	ds_write_b16 v7, v9 offset:26880
	v_add_u32_e32 v6, 4, v6
	v_add_u32_e32 v7, 2, v7
	s_mov_b64 exec, s[0:1]
	v_cmp_ge_u32_e32 vcc, v159, v5
	v_add_u16_e32 v9, 0x1b00, v130
	s_and_saveexec_b64 s[0:1], vcc
	ds_write_b32 v6, v159 offset:10496
	ds_write_b16 v7, v9 offset:26880
	v_add_u32_e32 v6, 4, v6
	v_add_u32_e32 v7, 2, v7
	s_mov_b64 exec, s[0:1]
	v_cmp_ge_u32_e32 vcc, v162, v5
	v_add_u16_e32 v9, 0x1c00, v130
	s_and_saveexec_b64 s[0:1], vcc
	ds_write_b32 v6, v162 offset:10496
	ds_write_b16 v7, v9 offset:26880
	v_add_u32_e32 v6, 4, v6
	v_add_u32_e32 v7, 2, v7
	s_mov_b64 exec, s[0:1]
	v_cmp_ge_u32_e32 vcc, v161, v5
	v_add_u16_e32 v9, 0x1d00, v130
	s_and_saveexec_b64 s[0:1], vcc
	ds_write_b32 v6, v161 offset:10496
	ds_write_b16 v7, v9 offset:26880
	v_add_u32_e32 v6, 4, v6
	v_add_u32_e32 v7, 2, v7
	s_mov_b64 exec, s[0:1]
	v_cmp_ge_u32_e32 vcc, v163, v5
	v_add_u16_e32 v9, 0x1e00, v130
	s_and_saveexec_b64 s[0:1], vcc
	ds_write_b32 v6, v163 offset:10496
	ds_write_b16 v7, v9 offset:26880
	v_add_u32_e32 v6, 4, v6
	v_add_u32_e32 v7, 2, v7
	s_mov_b64 exec, s[0:1]
	v_cmp_ge_u32_e32 vcc, v152, v5
	v_add_u16_e32 v9, 0x1f00, v130
	s_and_saveexec_b64 s[0:1], vcc
	ds_write_b32 v6, v152 offset:10496
	ds_write_b16 v7, v9 offset:26880
	v_add_u32_e32 v6, 4, v6
	v_add_u32_e32 v7, 2, v7
	s_mov_b64 exec, s[0:1]
	v_cmp_ge_u32_e32 vcc, v165, v5
	v_add_u16_e32 v9, 0x2000, v130
	s_and_saveexec_b64 s[0:1], vcc
	ds_write_b32 v6, v165 offset:10496
	ds_write_b16 v7, v9 offset:26880
	v_add_u32_e32 v6, 4, v6
	v_add_u32_e32 v7, 2, v7
	s_mov_b64 exec, s[0:1]
	v_cmp_ge_u32_e32 vcc, v164, v5
	v_add_u16_e32 v9, 0x2100, v130
	s_and_saveexec_b64 s[0:1], vcc
	ds_write_b32 v6, v164 offset:10496
	ds_write_b16 v7, v9 offset:26880
	v_add_u32_e32 v6, 4, v6
	v_add_u32_e32 v7, 2, v7
	s_mov_b64 exec, s[0:1]
	v_cmp_ge_u32_e32 vcc, v167, v5
	v_add_u16_e32 v9, 0x2200, v130
	s_and_saveexec_b64 s[0:1], vcc
	ds_write_b32 v6, v167 offset:10496
	ds_write_b16 v7, v9 offset:26880
	v_add_u32_e32 v6, 4, v6
	v_add_u32_e32 v7, 2, v7
	s_mov_b64 exec, s[0:1]
	v_cmp_ge_u32_e32 vcc, v166, v5
	v_add_u16_e32 v9, 0x2300, v130
	s_and_saveexec_b64 s[0:1], vcc
	ds_write_b32 v6, v166 offset:10496
	ds_write_b16 v7, v9 offset:26880
	v_add_u32_e32 v6, 4, v6
	v_add_u32_e32 v7, 2, v7
	s_mov_b64 exec, s[0:1]
	v_cmp_ge_u32_e32 vcc, v170, v5
	v_add_u16_e32 v9, 0x2400, v130
	s_and_saveexec_b64 s[0:1], vcc
	ds_write_b32 v6, v170 offset:10496
	ds_write_b16 v7, v9 offset:26880
	v_add_u32_e32 v6, 4, v6
	v_add_u32_e32 v7, 2, v7
	s_mov_b64 exec, s[0:1]
	v_cmp_ge_u32_e32 vcc, v169, v5
	v_add_u16_e32 v9, 0x2500, v130
	s_and_saveexec_b64 s[0:1], vcc
	ds_write_b32 v6, v169 offset:10496
	ds_write_b16 v7, v9 offset:26880
	v_add_u32_e32 v6, 4, v6
	v_add_u32_e32 v7, 2, v7
	s_mov_b64 exec, s[0:1]
	v_cmp_ge_u32_e32 vcc, v172, v5
	v_add_u16_e32 v9, 0x2600, v130
	s_and_saveexec_b64 s[0:1], vcc
	ds_write_b32 v6, v172 offset:10496
	ds_write_b16 v7, v9 offset:26880
	v_add_u32_e32 v6, 4, v6
	v_add_u32_e32 v7, 2, v7
	s_mov_b64 exec, s[0:1]
	v_cmp_ge_u32_e32 vcc, v171, v5
	v_add_u16_e32 v9, 0x2700, v130
	s_and_saveexec_b64 s[0:1], vcc
	ds_write_b32 v6, v171 offset:10496
	ds_write_b16 v7, v9 offset:26880
	v_add_u32_e32 v6, 4, v6
	v_add_u32_e32 v7, 2, v7
	s_mov_b64 exec, s[0:1]
	v_cmp_ge_u32_e32 vcc, v174, v5
	v_add_u16_e32 v9, 0x2800, v130
	s_and_saveexec_b64 s[0:1], vcc
	ds_write_b32 v6, v174 offset:10496
	ds_write_b16 v7, v9 offset:26880
	v_add_u32_e32 v6, 4, v6
	v_add_u32_e32 v7, 2, v7
	s_mov_b64 exec, s[0:1]
	v_cmp_ge_u32_e32 vcc, v173, v5
	v_add_u16_e32 v9, 0x2900, v130
	s_and_saveexec_b64 s[0:1], vcc
	ds_write_b32 v6, v173 offset:10496
	ds_write_b16 v7, v9 offset:26880
	v_add_u32_e32 v6, 4, v6
	v_add_u32_e32 v7, 2, v7
	s_mov_b64 exec, s[0:1]
	v_cmp_ge_u32_e32 vcc, v176, v5
	v_add_u16_e32 v9, 0x2a00, v130
	s_and_saveexec_b64 s[0:1], vcc
	ds_write_b32 v6, v176 offset:10496
	ds_write_b16 v7, v9 offset:26880
	v_add_u32_e32 v6, 4, v6
	v_add_u32_e32 v7, 2, v7
	s_mov_b64 exec, s[0:1]
	v_cmp_ge_u32_e32 vcc, v175, v5
	v_add_u16_e32 v9, 0x2b00, v130
	s_and_saveexec_b64 s[0:1], vcc
	ds_write_b32 v6, v175 offset:10496
	ds_write_b16 v7, v9 offset:26880
	v_add_u32_e32 v6, 4, v6
	v_add_u32_e32 v7, 2, v7
	s_mov_b64 exec, s[0:1]
	v_cmp_ge_u32_e32 vcc, v178, v5
	v_add_u16_e32 v9, 0x2c00, v130
	s_and_saveexec_b64 s[0:1], vcc
	ds_write_b32 v6, v178 offset:10496
	ds_write_b16 v7, v9 offset:26880
	v_add_u32_e32 v6, 4, v6
	v_add_u32_e32 v7, 2, v7
	s_mov_b64 exec, s[0:1]
	v_cmp_ge_u32_e32 vcc, v177, v5
	v_add_u16_e32 v9, 0x2d00, v130
	s_and_saveexec_b64 s[0:1], vcc
	ds_write_b32 v6, v177 offset:10496
	ds_write_b16 v7, v9 offset:26880
	v_add_u32_e32 v6, 4, v6
	v_add_u32_e32 v7, 2, v7
	s_mov_b64 exec, s[0:1]
	v_cmp_ge_u32_e32 vcc, v179, v5
	v_add_u16_e32 v9, 0x2e00, v130
	s_and_saveexec_b64 s[0:1], vcc
	ds_write_b32 v6, v179 offset:10496
	ds_write_b16 v7, v9 offset:26880
	v_add_u32_e32 v6, 4, v6
	v_add_u32_e32 v7, 2, v7
	s_mov_b64 exec, s[0:1]
	v_cmp_ge_u32_e32 vcc, v168, v5
	v_add_u16_e32 v9, 0x2f00, v130
	s_and_saveexec_b64 s[0:1], vcc
	ds_write_b32 v6, v168 offset:10496
	ds_write_b16 v7, v9 offset:26880
	v_add_u32_e32 v6, 4, v6
	v_add_u32_e32 v7, 2, v7
	s_mov_b64 exec, s[0:1]
	v_cmp_ge_u32_e32 vcc, v182, v5
	v_add_u16_e32 v9, 0x3000, v130
	s_and_saveexec_b64 s[0:1], vcc
	ds_write_b32 v6, v182 offset:10496
	ds_write_b16 v7, v9 offset:26880
	v_add_u32_e32 v6, 4, v6
	v_add_u32_e32 v7, 2, v7
	s_mov_b64 exec, s[0:1]
	v_cmp_ge_u32_e32 vcc, v181, v5
	v_add_u16_e32 v9, 0x3100, v130
	s_and_saveexec_b64 s[0:1], vcc
	ds_write_b32 v6, v181 offset:10496
	ds_write_b16 v7, v9 offset:26880
	v_add_u32_e32 v6, 4, v6
	v_add_u32_e32 v7, 2, v7
	s_mov_b64 exec, s[0:1]
	v_cmp_ge_u32_e32 vcc, v184, v5
	v_add_u16_e32 v9, 0x3200, v130
	s_and_saveexec_b64 s[0:1], vcc
	ds_write_b32 v6, v184 offset:10496
	ds_write_b16 v7, v9 offset:26880
	v_add_u32_e32 v6, 4, v6
	v_add_u32_e32 v7, 2, v7
	s_mov_b64 exec, s[0:1]
	v_cmp_ge_u32_e32 vcc, v183, v5
	v_add_u16_e32 v9, 0x3300, v130
	s_and_saveexec_b64 s[0:1], vcc
	ds_write_b32 v6, v183 offset:10496
	ds_write_b16 v7, v9 offset:26880
	v_add_u32_e32 v6, 4, v6
	v_add_u32_e32 v7, 2, v7
	s_mov_b64 exec, s[0:1]
	v_cmp_ge_u32_e32 vcc, v187, v5
	v_add_u16_e32 v9, 0x3400, v130
	s_and_saveexec_b64 s[0:1], vcc
	ds_write_b32 v6, v187 offset:10496
	ds_write_b16 v7, v9 offset:26880
	v_add_u32_e32 v6, 4, v6
	v_add_u32_e32 v7, 2, v7
	s_mov_b64 exec, s[0:1]
	v_cmp_ge_u32_e32 vcc, v186, v5
	v_add_u16_e32 v9, 0x3500, v130
	s_and_saveexec_b64 s[0:1], vcc
	ds_write_b32 v6, v186 offset:10496
	ds_write_b16 v7, v9 offset:26880
	v_add_u32_e32 v6, 4, v6
	v_add_u32_e32 v7, 2, v7
	s_mov_b64 exec, s[0:1]
	v_cmp_ge_u32_e32 vcc, v189, v5
	v_add_u16_e32 v9, 0x3600, v130
	s_and_saveexec_b64 s[0:1], vcc
	ds_write_b32 v6, v189 offset:10496
	ds_write_b16 v7, v9 offset:26880
	v_add_u32_e32 v6, 4, v6
	v_add_u32_e32 v7, 2, v7
	s_mov_b64 exec, s[0:1]
	v_cmp_ge_u32_e32 vcc, v188, v5
	v_add_u16_e32 v9, 0x3700, v130
	s_and_saveexec_b64 s[0:1], vcc
	ds_write_b32 v6, v188 offset:10496
	ds_write_b16 v7, v9 offset:26880
	v_add_u32_e32 v6, 4, v6
	v_add_u32_e32 v7, 2, v7
	s_mov_b64 exec, s[0:1]
	v_cmp_ge_u32_e32 vcc, v190, v5
	v_add_u16_e32 v9, 0x3800, v130
	s_and_saveexec_b64 s[0:1], vcc
	ds_write_b32 v6, v190 offset:10496
	ds_write_b16 v7, v9 offset:26880
	v_add_u32_e32 v6, 4, v6
	v_add_u32_e32 v7, 2, v7
	s_mov_b64 exec, s[0:1]
	v_cmp_ge_u32_e32 vcc, v53, v5
	v_add_u16_e32 v9, 0x3900, v130
	s_and_saveexec_b64 s[0:1], vcc
	ds_write_b32 v6, v53 offset:10496
	ds_write_b16 v7, v9 offset:26880
	v_add_u32_e32 v6, 4, v6
	v_add_u32_e32 v7, 2, v7
	s_mov_b64 exec, s[0:1]
	v_cmp_ge_u32_e32 vcc, v192, v5
	v_add_u16_e32 v9, 0x3a00, v130
	s_and_saveexec_b64 s[0:1], vcc
	ds_write_b32 v6, v192 offset:10496
	ds_write_b16 v7, v9 offset:26880
	v_add_u32_e32 v6, 4, v6
	v_add_u32_e32 v7, 2, v7
	s_mov_b64 exec, s[0:1]
	v_cmp_ge_u32_e32 vcc, v191, v5
	v_add_u16_e32 v9, 0x3b00, v130
	s_and_saveexec_b64 s[0:1], vcc
	ds_write_b32 v6, v191 offset:10496
	ds_write_b16 v7, v9 offset:26880
	v_add_u32_e32 v6, 4, v6
	v_add_u32_e32 v7, 2, v7
	s_mov_b64 exec, s[0:1]
	v_cmp_ge_u32_e32 vcc, v3, v5
	v_add_u16_e32 v9, 0x3c00, v130
	s_and_saveexec_b64 s[0:1], vcc
	ds_write_b32 v6, v3 offset:10496
	ds_write_b16 v7, v9 offset:26880
	v_add_u32_e32 v6, 4, v6
	v_add_u32_e32 v7, 2, v7
	s_mov_b64 exec, s[0:1]
	v_cmp_ge_u32_e32 vcc, v2, v5
	v_add_u16_e32 v9, 0x3d00, v130
	s_and_saveexec_b64 s[0:1], vcc
	ds_write_b32 v6, v2 offset:10496
	ds_write_b16 v7, v9 offset:26880
	v_add_u32_e32 v6, 4, v6
	v_add_u32_e32 v7, 2, v7
	s_mov_b64 exec, s[0:1]
	v_cmp_ge_u32_e32 vcc, v4, v5
	v_add_u16_e32 v9, 0x3e00, v130
	s_and_saveexec_b64 s[0:1], vcc
	ds_write_b32 v6, v4 offset:10496
	ds_write_b16 v7, v9 offset:26880
	v_add_u32_e32 v6, 4, v6
	v_add_u32_e32 v7, 2, v7
	s_mov_b64 exec, s[0:1]
	v_cmp_ge_u32_e32 vcc, v185, v5
	v_add_u16_e32 v9, 0x3f00, v130
	s_and_saveexec_b64 s[0:1], vcc
	ds_write_b32 v6, v185 offset:10496
	ds_write_b16 v7, v9 offset:26880
	v_add_u32_e32 v6, 4, v6
	v_add_u32_e32 v7, 2, v7
	s_mov_b64 exec, s[0:1]
	s_branch .LBB0_1337

.LBB0_1272:
	v_cmp_gt_u32_e32 vcc, s74, v6
	s_andn2_b64 s[0:1], s[0:1], exec
	s_and_b64 s[10:11], vcc, exec
	s_or_b64 s[0:1], s[0:1], s[10:11]
	v_mov_b32_e32 v5, v6
	s_or_b64 exec, exec, s[8:9]
	s_and_saveexec_b64 s[8:9], s[0:1]
	s_cbranch_execnz .LBB0_1204
	s_branch .LBB0_1205
.LBB0_1337:
	s_or_b64 exec, exec, s[0:1]
	s_ashr_i32 s85, s83, 8
	s_cmpk_lt_u32 s83, 0x100
	s_cselect_b64 vcc, -1, 0
	s_lshl_b32 s0, s85, 13
	v_and_b32_e32 v9, 0xff, v129
	v_cndmask_b32_e32 v1, v105, v104, vcc
	s_add_i32 s0, s0, 0
	v_cmp_lt_i32_e32 vcc, v9, v1
	v_mov_b32_e32 v16, 0
	v_lshl_add_u32 v0, v9, 2, s0
	v_mov_b32_e32 v17, 0
	s_waitcnt vmcnt(0) lgkmcnt(0)
	s_barrier
	s_cmp_lg_u32 s82, 0
	s_cbranch_scc1 .Lpf_skip
	s_lshl_b32 s90, s2, 17
	s_lshl_b32 s91, s84, 8
	s_add_u32 s90, s90, s91
	s_add_u32 s90, s28, s90
	s_addc_u32 s91, s29, 0
	global_load_dword v133, v243, s[90:91] sc1
	global_load_dword v132, v243, s[90:91] offset:2048 sc1
	s_add_u32 s90, s90, 0x1000
	s_addc_u32 s91, s91, 0
	global_load_dword v135, v243, s[90:91] sc1
	global_load_dword v134, v243, s[90:91] offset:2048 sc1
	s_add_u32 s90, s90, 0x1000
	s_addc_u32 s91, s91, 0
	global_load_dword v138, v243, s[90:91] sc1
	global_load_dword v137, v243, s[90:91] offset:2048 sc1
	s_add_u32 s90, s90, 0x1000
	s_addc_u32 s91, s91, 0
	global_load_dword v140, v243, s[90:91] sc1
	global_load_dword v139, v243, s[90:91] offset:2048 sc1
	s_add_u32 s90, s90, 0x1000
	s_addc_u32 s91, s91, 0
	s_cmpk_gt_i32 s81, 8
	s_cbranch_scc0 .Lpf_end
	global_load_dword v142, v243, s[90:91] sc1
	global_load_dword v141, v243, s[90:91] offset:2048 sc1
	s_add_u32 s90, s90, 0x1000
	s_addc_u32 s91, s91, 0
	global_load_dword v144, v243, s[90:91] sc1
	global_load_dword v143, v243, s[90:91] offset:2048 sc1
	s_add_u32 s90, s90, 0x1000
	s_addc_u32 s91, s91, 0
	global_load_dword v146, v243, s[90:91] sc1
	global_load_dword v145, v243, s[90:91] offset:2048 sc1
	s_add_u32 s90, s90, 0x1000
	s_addc_u32 s91, s91, 0
	global_load_dword v147, v243, s[90:91] sc1
	global_load_dword v136, v243, s[90:91] offset:2048 sc1
	s_add_u32 s90, s90, 0x1000
	s_addc_u32 s91, s91, 0
	s_cmpk_gt_i32 s81, 16
	s_cbranch_scc0 .Lpf_end
	global_load_dword v149, v243, s[90:91] sc1
	global_load_dword v148, v243, s[90:91] offset:2048 sc1
	s_add_u32 s90, s90, 0x1000
	s_addc_u32 s91, s91, 0
	global_load_dword v151, v243, s[90:91] sc1
	global_load_dword v150, v243, s[90:91] offset:2048 sc1
	s_add_u32 s90, s90, 0x1000
	s_addc_u32 s91, s91, 0
	global_load_dword v154, v243, s[90:91] sc1
	global_load_dword v153, v243, s[90:91] offset:2048 sc1
	s_add_u32 s90, s90, 0x1000
	s_addc_u32 s91, s91, 0
	global_load_dword v156, v243, s[90:91] sc1
	global_load_dword v155, v243, s[90:91] offset:2048 sc1
	s_add_u32 s90, s90, 0x1000
	s_addc_u32 s91, s91, 0
	s_cmpk_gt_i32 s81, 24
	s_cbranch_scc0 .Lpf_end
	global_load_dword v158, v243, s[90:91] sc1
	global_load_dword v157, v243, s[90:91] offset:2048 sc1
	s_add_u32 s90, s90, 0x1000
	s_addc_u32 s91, s91, 0
	global_load_dword v160, v243, s[90:91] sc1
	global_load_dword v159, v243, s[90:91] offset:2048 sc1
	s_add_u32 s90, s90, 0x1000
	s_addc_u32 s91, s91, 0
	global_load_dword v162, v243, s[90:91] sc1
	global_load_dword v161, v243, s[90:91] offset:2048 sc1
	s_add_u32 s90, s90, 0x1000
	s_addc_u32 s91, s91, 0
	global_load_dword v163, v243, s[90:91] sc1
	global_load_dword v152, v243, s[90:91] offset:2048 sc1
	s_add_u32 s90, s90, 0x1000
	s_addc_u32 s91, s91, 0
	s_cmpk_gt_i32 s81, 32
	s_cbranch_scc0 .Lpf_end
	global_load_dword v165, v243, s[90:91] sc1
	global_load_dword v164, v243, s[90:91] offset:2048 sc1
	s_add_u32 s90, s90, 0x1000
	s_addc_u32 s91, s91, 0
	global_load_dword v167, v243, s[90:91] sc1
	global_load_dword v166, v243, s[90:91] offset:2048 sc1
	s_add_u32 s90, s90, 0x1000
	s_addc_u32 s91, s91, 0
	global_load_dword v170, v243, s[90:91] sc1
	global_load_dword v169, v243, s[90:91] offset:2048 sc1
	s_add_u32 s90, s90, 0x1000
	s_addc_u32 s91, s91, 0
	global_load_dword v172, v243, s[90:91] sc1
	global_load_dword v171, v243, s[90:91] offset:2048 sc1
	s_add_u32 s90, s90, 0x1000
	s_addc_u32 s91, s91, 0
	s_cmpk_gt_i32 s81, 40
	s_cbranch_scc0 .Lpf_end
	global_load_dword v174, v243, s[90:91] sc1
	global_load_dword v173, v243, s[90:91] offset:2048 sc1
	s_add_u32 s90, s90, 0x1000
	s_addc_u32 s91, s91, 0
	global_load_dword v176, v243, s[90:91] sc1
	global_load_dword v175, v243, s[90:91] offset:2048 sc1
	s_add_u32 s90, s90, 0x1000
	s_addc_u32 s91, s91, 0
	global_load_dword v178, v243, s[90:91] sc1
	global_load_dword v177, v243, s[90:91] offset:2048 sc1
	s_add_u32 s90, s90, 0x1000
	s_addc_u32 s91, s91, 0
	global_load_dword v179, v243, s[90:91] sc1
	global_load_dword v168, v243, s[90:91] offset:2048 sc1
	s_add_u32 s90, s90, 0x1000
	s_addc_u32 s91, s91, 0
	s_cmpk_gt_i32 s81, 48
	s_cbranch_scc0 .Lpf_end
	global_load_dword v182, v243, s[90:91] sc1
	global_load_dword v181, v243, s[90:91] offset:2048 sc1
	s_add_u32 s90, s90, 0x1000
	s_addc_u32 s91, s91, 0
	global_load_dword v184, v243, s[90:91] sc1
	global_load_dword v183, v243, s[90:91] offset:2048 sc1
	s_add_u32 s90, s90, 0x1000
	s_addc_u32 s91, s91, 0
	global_load_dword v187, v243, s[90:91] sc1
	global_load_dword v186, v243, s[90:91] offset:2048 sc1
	s_add_u32 s90, s90, 0x1000
	s_addc_u32 s91, s91, 0
	global_load_dword v189, v243, s[90:91] sc1
	global_load_dword v188, v243, s[90:91] offset:2048 sc1
	s_add_u32 s90, s90, 0x1000
	s_addc_u32 s91, s91, 0
	s_cmpk_gt_i32 s81, 56
	s_cbranch_scc0 .Lpf_end
	global_load_dword v190, v243, s[90:91] sc1
	global_load_dword v53, v243, s[90:91] offset:2048 sc1
	s_add_u32 s90, s90, 0x1000
	s_addc_u32 s91, s91, 0
	global_load_dword v192, v243, s[90:91] sc1
	global_load_dword v191, v243, s[90:91] offset:2048 sc1
	s_add_u32 s90, s90, 0x1000
	s_addc_u32 s91, s91, 0
	global_load_dword v244, v243, s[90:91] sc1
	global_load_dword v245, v243, s[90:91] offset:2048 sc1
	s_add_u32 s90, s90, 0x1000
	s_addc_u32 s91, s91, 0
	global_load_dword v246, v243, s[90:91] sc1
	global_load_dword v185, v243, s[90:91] offset:2048 sc1
	s_add_u32 s90, s90, 0x1000
	s_addc_u32 s91, s91, 0
